# nt_p0a_loads_and_stores
# speedup vs baseline: 1.0057x; 1.0057x over previous
.LBB0_34:
	s_lshl_b32 s28, s3, 1
	s_lshl_b32 s29, s11, 1
	v_or_b32_e32 v15, s28, v1
	v_or_b32_e32 v77, s29, v2
	s_add_i32 s30, s28, 4
	s_add_i32 s31, s29, 4
	s_add_i32 s34, s28, 8
	s_add_i32 s35, s29, 8
	s_add_i32 s36, s28, 12
	s_add_i32 s37, s29, 12
	s_add_i32 s38, s28, 16
	s_add_i32 s39, s29, 16
	s_add_i32 s40, s28, 20
	s_add_i32 s41, s29, 20
	s_add_i32 s42, s28, 24
	s_add_i32 s43, s29, 24
	s_add_i32 s28, s28, 28
	s_add_i32 s29, s29, 28
	v_add_u32_e32 v16, s9, v15
	v_add_u32_e32 v18, s10, v77
	v_or_b32_e32 v79, s30, v1
	v_or_b32_e32 v80, s31, v2
	v_or_b32_e32 v81, s34, v1
	v_or_b32_e32 v82, s35, v2
	v_or_b32_e32 v83, s36, v1
	v_or_b32_e32 v84, s37, v2
	v_or_b32_e32 v85, s38, v1
	v_or_b32_e32 v86, s39, v2
	v_or_b32_e32 v87, s40, v1
	v_or_b32_e32 v88, s41, v2
	v_or_b32_e32 v89, s42, v1
	v_or_b32_e32 v90, s43, v2
	v_or_b32_e32 v91, s28, v1
	v_or_b32_e32 v92, s29, v2
	v_ashrrev_i32_e32 v23, 31, v18
	v_ashrrev_i32_e32 v21, 31, v16
	v_mad_u64_u32 v[16:17], s[28:29], s12, v16, 0
	v_mad_u64_u32 v[18:19], s[28:29], s27, v18, 0
	v_add_u32_e32 v24, s9, v79
	v_add_u32_e32 v26, s10, v80
	v_add_u32_e32 v28, s9, v81
	v_add_u32_e32 v30, s10, v82
	v_add_u32_e32 v32, s9, v83
	v_add_u32_e32 v34, s10, v84
	v_add_u32_e32 v36, s9, v85
	v_add_u32_e32 v38, s10, v86
	v_add_u32_e32 v40, s9, v87
	v_add_u32_e32 v42, s10, v88
	v_add_u32_e32 v44, s9, v89
	v_add_u32_e32 v46, s10, v90
	v_add_u32_e32 v48, s9, v91
	v_add_u32_e32 v50, s10, v92
	v_mov_b32_e32 v20, v17
	v_mov_b32_e32 v22, v19
	v_ashrrev_i32_e32 v53, 31, v26
	v_ashrrev_i32_e32 v55, 31, v24
	v_mad_u64_u32 v[24:25], s[28:29], s12, v24, 0
	v_mad_u64_u32 v[26:27], s[28:29], s27, v26, 0
	v_ashrrev_i32_e32 v57, 31, v30
	v_ashrrev_i32_e32 v59, 31, v28
	v_mad_u64_u32 v[28:29], s[28:29], s12, v28, 0
	v_mad_u64_u32 v[30:31], s[28:29], s27, v30, 0
	v_ashrrev_i32_e32 v61, 31, v34
	v_ashrrev_i32_e32 v63, 31, v32
	v_mad_u64_u32 v[32:33], s[28:29], s12, v32, 0
	v_mad_u64_u32 v[34:35], s[28:29], s27, v34, 0
	v_ashrrev_i32_e32 v65, 31, v38
	v_ashrrev_i32_e32 v67, 31, v36
	v_mad_u64_u32 v[36:37], s[28:29], s12, v36, 0
	v_mad_u64_u32 v[38:39], s[28:29], s27, v38, 0
	v_ashrrev_i32_e32 v69, 31, v42
	v_ashrrev_i32_e32 v71, 31, v40
	v_mad_u64_u32 v[40:41], s[28:29], s12, v40, 0
	v_mad_u64_u32 v[42:43], s[28:29], s27, v42, 0
	v_ashrrev_i32_e32 v73, 31, v46
	v_ashrrev_i32_e32 v75, 31, v44
	v_mad_u64_u32 v[44:45], s[28:29], s12, v44, 0
	v_mad_u64_u32 v[46:47], s[28:29], s27, v46, 0
	v_ashrrev_i32_e32 v93, 31, v50
	v_ashrrev_i32_e32 v94, 31, v48
	v_mad_u64_u32 v[48:49], s[28:29], s12, v48, 0
	v_mad_u64_u32 v[50:51], s[28:29], s27, v50, 0
	v_mad_u64_u32 v[20:21], s[28:29], s12, v21, v[20:21]
	v_mad_u64_u32 v[22:23], s[28:29], s27, v23, v[22:23]
	v_mov_b32_e32 v52, v25
	v_mov_b32_e32 v54, v27
	v_mov_b32_e32 v56, v29
	v_mov_b32_e32 v58, v31
	v_mov_b32_e32 v60, v33
	v_mov_b32_e32 v62, v35
	v_mov_b32_e32 v64, v37
	v_mov_b32_e32 v66, v39
	v_mov_b32_e32 v68, v41
	v_mov_b32_e32 v70, v43
	v_mov_b32_e32 v72, v45
	v_mov_b32_e32 v74, v47
	v_mov_b32_e32 v76, v49
	v_mov_b32_e32 v78, v51
	v_mov_b32_e32 v17, v20
	v_mov_b32_e32 v19, v22
	v_mad_u64_u32 v[20:21], s[28:29], s12, v55, v[52:53]
	v_mad_u64_u32 v[22:23], s[28:29], s27, v53, v[54:55]
	v_mad_u64_u32 v[52:53], s[28:29], s12, v59, v[56:57]
	v_mad_u64_u32 v[54:55], s[28:29], s27, v57, v[58:59]
	v_mad_u64_u32 v[56:57], s[28:29], s12, v63, v[60:61]
	v_mad_u64_u32 v[58:59], s[28:29], s27, v61, v[62:63]
	v_mad_u64_u32 v[60:61], s[28:29], s12, v67, v[64:65]
	v_mad_u64_u32 v[62:63], s[28:29], s27, v65, v[66:67]
	v_mad_u64_u32 v[64:65], s[28:29], s12, v71, v[68:69]
	v_mad_u64_u32 v[66:67], s[28:29], s27, v69, v[70:71]
	v_mad_u64_u32 v[68:69], s[28:29], s12, v75, v[72:73]
	v_mad_u64_u32 v[70:71], s[28:29], s27, v73, v[74:75]
	v_mad_u64_u32 v[72:73], s[28:29], s12, v94, v[76:77]
	v_mad_u64_u32 v[74:75], s[28:29], s27, v93, v[78:79]
	v_mov_b32_e32 v25, v20
	v_mov_b32_e32 v27, v22
	v_mov_b32_e32 v29, v52
	v_mov_b32_e32 v31, v54
	v_mov_b32_e32 v33, v56
	v_mov_b32_e32 v35, v58
	v_mov_b32_e32 v37, v60
	v_mov_b32_e32 v39, v62
	v_mov_b32_e32 v41, v64
	v_mov_b32_e32 v43, v66
	v_mov_b32_e32 v45, v68
	v_mov_b32_e32 v47, v70
	v_lshl_add_u64 v[18:19], v[18:19], 2, v[10:11]
	v_mov_b32_e32 v49, v72
	v_mov_b32_e32 v51, v74
	v_lshl_add_u64 v[16:17], v[16:17], 2, v[10:11]
	v_lshl_add_u64 v[20:21], v[26:27], 2, v[10:11]
	v_lshl_add_u64 v[22:23], v[24:25], 2, v[10:11]
	v_lshl_add_u64 v[24:25], v[30:31], 2, v[10:11]
	v_lshl_add_u64 v[26:27], v[28:29], 2, v[10:11]
	v_lshl_add_u64 v[28:29], v[34:35], 2, v[10:11]
	v_lshl_add_u64 v[30:31], v[32:33], 2, v[10:11]
	v_lshl_add_u64 v[32:33], v[38:39], 2, v[10:11]
	v_lshl_add_u64 v[34:35], v[36:37], 2, v[10:11]
	v_lshl_add_u64 v[36:37], v[42:43], 2, v[10:11]
	v_lshl_add_u64 v[38:39], v[40:41], 2, v[10:11]
	v_lshl_add_u64 v[40:41], v[46:47], 2, v[10:11]
	v_lshl_add_u64 v[42:43], v[44:45], 2, v[10:11]
	v_lshl_add_u64 v[44:45], v[50:51], 2, v[10:11]
	v_lshl_add_u64 v[46:47], v[48:49], 2, v[10:11]
	global_load_dword v48, v[18:19], off nt
	global_load_dword v49, v[16:17], off nt
	global_load_dword v50, v[20:21], off nt
	global_load_dword v51, v[22:23], off nt
	global_load_dword v52, v[24:25], off nt
	global_load_dword v53, v[26:27], off nt
	global_load_dword v54, v[28:29], off nt
	global_load_dword v55, v[30:31], off nt
	global_load_dword v56, v[32:33], off nt
	global_load_dword v57, v[34:35], off nt
	global_load_dword v58, v[36:37], off nt
	global_load_dword v59, v[38:39], off nt
	global_load_dword v60, v[40:41], off nt
	global_load_dword v61, v[42:43], off nt
	global_load_dword v62, v[44:45], off nt
	global_load_dword v63, v[46:47], off nt
	s_add_i32 s11, s11, 16
	s_add_i32 s3, s3, 16
	s_add_i32 s13, s13, -16
	v_mad_u64_u32 v[16:17], s[28:29], v77, s26, v[6:7]
	s_cmp_lg_u32 s13, 0
	v_mad_u64_u32 v[18:19], s[28:29], v15, s26, v[6:7]
	v_mad_u64_u32 v[20:21], s[28:29], v80, s26, v[6:7]
	v_mad_u64_u32 v[22:23], s[28:29], v79, s26, v[6:7]
	v_mad_u64_u32 v[24:25], s[28:29], v82, s26, v[6:7]
	v_mad_u64_u32 v[26:27], s[28:29], v81, s26, v[6:7]
	v_mad_u64_u32 v[28:29], s[28:29], v84, s26, v[6:7]
	v_mad_u64_u32 v[30:31], s[28:29], v83, s26, v[6:7]
	v_mad_u64_u32 v[32:33], s[28:29], v86, s26, v[6:7]
	v_mad_u64_u32 v[34:35], s[28:29], v85, s26, v[6:7]
	v_mad_u64_u32 v[36:37], s[28:29], v88, s26, v[6:7]
	v_mad_u64_u32 v[38:39], s[28:29], v87, s26, v[6:7]
	v_mad_u64_u32 v[40:41], s[28:29], v90, s26, v[6:7]
	v_mad_u64_u32 v[42:43], s[28:29], v89, s26, v[6:7]
	v_mad_u64_u32 v[44:45], s[28:29], v92, s26, v[6:7]
	v_mad_u64_u32 v[46:47], s[28:29], v91, s26, v[6:7]
	s_waitcnt vmcnt(15)
	ds_write_b32 v16, v48
	s_waitcnt vmcnt(14)
	ds_write_b32 v18, v49
	s_waitcnt vmcnt(13)
	ds_write_b32 v20, v50
	s_waitcnt vmcnt(12)
	ds_write_b32 v22, v51
	s_waitcnt vmcnt(11)
	ds_write_b32 v24, v52
	s_waitcnt vmcnt(10)
	ds_write_b32 v26, v53
	s_waitcnt vmcnt(9)
	ds_write_b32 v28, v54
	s_waitcnt vmcnt(8)
	ds_write_b32 v30, v55
	s_waitcnt vmcnt(7)
	ds_write_b32 v32, v56
	s_waitcnt vmcnt(6)
	ds_write_b32 v34, v57
	s_waitcnt vmcnt(5)
	ds_write_b32 v36, v58
	s_waitcnt vmcnt(4)
	ds_write_b32 v38, v59
	s_waitcnt vmcnt(3)
	ds_write_b32 v40, v60
	s_waitcnt vmcnt(2)
	ds_write_b32 v42, v61
	s_waitcnt vmcnt(1)
	ds_write_b32 v44, v62
	s_waitcnt vmcnt(0)
	ds_write_b32 v46, v63
	s_cbranch_scc1 .LBB0_34
	s_lshl_b64 s[6:7], s[6:7], 1
	s_waitcnt lgkmcnt(0)
	s_add_u32 s3, s4, s6
	s_addc_u32 s6, s5, s7
	s_ashr_i32 s11, s10, 31
	ds_read2_b32 v[10:11], v7 offset1:33
	s_lshl_b64 s[4:5], s[10:11], 1
	s_waitcnt lgkmcnt(0)
	v_cvt_pk_bf16_f32 v16, v10, v11
	ds_read2_b32 v[10:11], v7 offset0:66 offset1:99
	s_add_u32 s4, s3, s4
	s_waitcnt lgkmcnt(0)
	v_cvt_pk_bf16_f32 v17, v10, v11
	ds_read2_b32 v[10:11], v7 offset0:132 offset1:165
	v_or_b32_e32 v15, s8, v3
	s_addc_u32 s5, s6, s5
	v_mul_hi_i32_i24_e32 v21, s2, v15
	v_mul_i32_i24_e32 v20, s2, v15
	s_waitcnt lgkmcnt(0)
	v_cvt_pk_bf16_f32 v18, v10, v11
	ds_read2_b32 v[10:11], v7 offset0:198 offset1:231
	v_lshl_add_u64 v[22:23], s[4:5], 0, v[4:5]
	s_waitcnt lgkmcnt(0)
	v_cvt_pk_bf16_f32 v19, v10, v11
	ds_read2_b32 v[10:11], v7 offset0:8 offset1:41
	v_lshl_add_u64 v[20:21], v[20:21], 1, v[22:23]
	global_store_dwordx4 v[20:21], v[16:19], off nt
	v_or_b32_e32 v15, s8, v12
	v_mul_hi_i32_i24_e32 v21, s2, v15
	s_waitcnt lgkmcnt(0)
	v_cvt_pk_bf16_f32 v16, v10, v11
	ds_read2_b32 v[10:11], v7 offset0:74 offset1:107
	s_waitcnt lgkmcnt(0)
	v_cvt_pk_bf16_f32 v17, v10, v11
	ds_read2_b32 v[10:11], v7 offset0:140 offset1:173
	s_waitcnt lgkmcnt(0)
	v_cvt_pk_bf16_f32 v18, v10, v11
	ds_read2_b32 v[10:11], v7 offset0:206 offset1:239
	v_mul_i32_i24_e32 v20, s2, v15
	s_waitcnt lgkmcnt(0)
	v_cvt_pk_bf16_f32 v19, v10, v11
	ds_read2_b32 v[10:11], v7 offset0:16 offset1:49
	v_lshl_add_u64 v[20:21], v[20:21], 1, v[22:23]
	global_store_dwordx4 v[20:21], v[16:19], off nt
	v_or_b32_e32 v15, s8, v13
	v_mul_hi_i32_i24_e32 v21, s2, v15
	s_waitcnt lgkmcnt(0)
	v_cvt_pk_bf16_f32 v16, v10, v11
	ds_read2_b32 v[10:11], v7 offset0:82 offset1:115
	s_waitcnt lgkmcnt(0)
	v_cvt_pk_bf16_f32 v17, v10, v11
	ds_read2_b32 v[10:11], v7 offset0:148 offset1:181
	s_waitcnt lgkmcnt(0)
	v_cvt_pk_bf16_f32 v18, v10, v11
	ds_read2_b32 v[10:11], v7 offset0:214 offset1:247
	v_mul_i32_i24_e32 v20, s2, v15
	s_waitcnt lgkmcnt(0)
	v_cvt_pk_bf16_f32 v19, v10, v11
	ds_read2_b32 v[10:11], v7 offset0:24 offset1:57
	v_lshl_add_u64 v[20:21], v[20:21], 1, v[22:23]
	v_or_b32_e32 v15, s8, v14
	global_store_dwordx4 v[20:21], v[16:19], off nt
	v_mul_hi_i32_i24_e32 v21, s2, v15
	v_mul_i32_i24_e32 v20, s2, v15
	s_waitcnt lgkmcnt(0)
	v_cvt_pk_bf16_f32 v16, v10, v11
	ds_read2_b32 v[10:11], v7 offset0:90 offset1:123
	s_waitcnt lgkmcnt(0)
	v_cvt_pk_bf16_f32 v17, v10, v11
	ds_read2_b32 v[10:11], v7 offset0:156 offset1:189
	v_lshl_add_u64 v[20:21], v[20:21], 1, v[22:23]
	s_waitcnt lgkmcnt(0)
	v_cvt_pk_bf16_f32 v18, v10, v11
	ds_read2_b32 v[10:11], v7 offset0:222 offset1:255
	s_waitcnt lgkmcnt(0)
	v_cvt_pk_bf16_f32 v19, v10, v11
	global_store_dwordx4 v[20:21], v[16:19], off nt
	s_waitcnt lgkmcnt(0)
	s_add_i32 s14, s14, s15
	s_cmp_lt_i32 s14, 0x1e800
	s_cbranch_scc1 .LBB0_11
	s_branch .LBB0_37
